# L1 attention: first K/V tile of each unit fetched at the unit top, hidden behind the Q preparation
# speedup vs baseline: 1.0051x; 1.0051x over previous
; template <int DQK, int MODE>
; DI void attn_phase(const bf16_t* __restrict__ QK, int ldq, const bf16_t* __restrict__ Vt, int VC, bf16_t* __restrict__ O, int ldo, int nhu, bool skip_ctx, const float* __restrict__ qgain, const f32x2* __restrict__ rope, float qscale, char* shm) {
;     ...
;         if (u < nlat) { qt = 1 + (u & 7); hu = (u >> 3) % nhu; b = (u >> 3) / nhu; } else { const int v = u - nlat; qt = 0; hu = v % nhu; b = v / nhu; }
;         const int qoff = hu * DQK, koff = 1024 + (MODE == 0 ? hu * 64 : (hu >> 2) * 128), voff = (MODE == 0 ? (hu >> 1) : (hu >> 2)) * 128, ooff = hu * 128;
;         const int nkt = qt == 0 ? 4 : 36;
;         const size_t qrow = (size_t)b * LT + qt * 256 + w * 32 + r;
;         bf16x8 qf[DQK / 16];
; #pragma unroll
;         for (int ks = 0; ks < DQK / 16; ++ks) qf[ks] = *(const bf16x8*)(QK + qrow * ldq + qoff + ks * 16 + h * 8);
;     ...
;         const bf16_t* kbase = QK + (size_t)b * LT * ldq + koff; const bf16_t* vbase = Vt + ((size_t)b * VC + voff) * LT;
;         u32x4 kreg[NKC], vreg[2];
;     ...
;         ATT_LOAD(0);
.LBB0_1292:
	s_lshl_b32 s12, s31, 6
	s_cmp_lg_u32 s0, 0
	s_cselect_b64 s[14:15], -1, 0
	s_mul_i32 s11, s10, 0x900
	s_lshl_b32 s13, s0, 8
	s_mul_hi_i32 s1, s10, 0x900
	s_add_u32 s34, s13, s11
	s_addc_u32 s35, 0, s1
	v_lshl_add_u64 v[0:1], s[34:35], 0, v[124:125]
	v_lshlrev_b64 v[148:149], 12, v[0:1]
	s_ashr_i32 s13, s12, 31
	s_mul_i32 s98, s10, 0x900000
	s_mul_hi_i32 s99, s10, 0x900000
	s_add_u32 s98, s98, s96
	s_addc_u32 s99, s99, s97
	s_lshl_b64 s[100:101], s[12:13], 1
	s_add_u32 s98, s98, s100
	s_addc_u32 s99, s99, s101
	v_lshl_add_u64 v[244:245], s[98:99], 0, v[132:133]
	v_lshl_add_u64 v[244:245], v[134:135], 1, v[244:245]
	global_load_dwordx4 v[232:235], v[244:245], off offset:2048
	s_lshl_b32 s98, s10, 10
	s_and_b32 s99, s12, 0xffffff80
	s_add_i32 s98, s98, s99
	v_mad_u64_u32 v[248:249], s[100:101], s98, v165, v[136:137]
	v_lshl_add_u64 v[250:251], v[248:249], 0, v[138:139]
	global_load_dwordx4 v[236:239], v[250:251], off
	v_lshl_add_u64 v[250:251], v[248:249], 0, v[140:141]
	global_load_dwordx4 v[240:243], v[250:251], off
	v_lshl_add_u64 v[0:1], s[96:97], 0, v[148:149]
	v_lshl_add_u64 v[0:1], s[12:13], 1, v[0:1]
	v_lshl_add_u64 v[0:1], v[0:1], 0, v[128:129]
	global_load_dwordx4 v[2:5], v[0:1], off offset:64
	global_load_dwordx4 v[18:21], v[0:1], off
	global_load_dwordx4 v[12:15], v[0:1], off offset:96
	global_load_dwordx4 v[38:41], v[0:1], off offset:32
	v_and_or_b32 v0, s12, 64, v126
	v_readlane_b32 s36, v254, 7
	v_readlane_b32 s44, v254, 15
	v_ashrrev_i32_e32 v1, 31, v0
	v_readlane_b32 s45, v254, 16
	s_max_u32 s1, s0, 1
	s_cmp_eq_u32 s0, 0
	v_lshl_add_u64 v[0:1], v[0:1], 2, s[44:45]
	global_load_dword v200, v[0:1], off
	global_load_dword v201, v[0:1], off offset:128
	global_load_dword v202, v[0:1], off offset:4
	global_load_dword v203, v[0:1], off offset:132
	global_load_dword v204, v[0:1], off offset:8
	global_load_dword v205, v[0:1], off offset:136
	global_load_dword v206, v[0:1], off offset:12
	global_load_dword v207, v[0:1], off offset:140
	global_load_dword v208, v[0:1], off offset:16
	global_load_dword v209, v[0:1], off offset:144
	global_load_dword v210, v[0:1], off offset:20
	global_load_dword v211, v[0:1], off offset:148
	global_load_dword v212, v[0:1], off offset:24
	global_load_dword v213, v[0:1], off offset:152
	global_load_dword v214, v[0:1], off offset:28
	global_load_dword v215, v[0:1], off offset:156
	global_load_dword v216, v[0:1], off offset:64
	global_load_dword v217, v[0:1], off offset:192
	global_load_dword v218, v[0:1], off offset:68
	global_load_dword v219, v[0:1], off offset:196
	global_load_dword v220, v[0:1], off offset:72
	global_load_dword v221, v[0:1], off offset:200
	global_load_dword v222, v[0:1], off offset:76
	global_load_dword v223, v[0:1], off offset:204
	global_load_dword v224, v[0:1], off offset:80
	global_load_dword v225, v[0:1], off offset:208
	global_load_dword v226, v[0:1], off offset:84
	global_load_dword v227, v[0:1], off offset:212
	global_load_dword v228, v[0:1], off offset:88
	global_load_dword v229, v[0:1], off offset:216
	global_load_dword v246, v[0:1], off offset:92
	global_load_dword v247, v[0:1], off offset:220
	v_lshl_add_u32 v166, s1, 8, v157
	v_ashrrev_i32_e32 v167, 31, v166
	v_lshlrev_b64 v[166:167], 8, v[166:167]
	v_lshl_add_u64 v[166:167], v[130:131], 0, v[166:167]
	global_load_dwordx4 v[168:171], v[166:167], off
	global_load_dwordx4 v[172:175], v[166:167], off offset:16
	global_load_dwordx4 v[176:179], v[166:167], off offset:32
	global_load_dwordx4 v[180:183], v[166:167], off offset:48
	global_load_dwordx4 v[184:187], v[166:167], off offset:128
	global_load_dwordx4 v[188:191], v[166:167], off offset:144
	global_load_dwordx4 v[192:195], v[166:167], off offset:160
	global_load_dwordx4 v[196:199], v[166:167], off offset:176
	v_readlane_b32 s37, v254, 8
	v_readlane_b32 s38, v254, 9
	v_readlane_b32 s39, v254, 10
	v_readlane_b32 s40, v254, 11
	v_readlane_b32 s41, v254, 12
	v_readlane_b32 s42, v254, 13
	v_readlane_b32 s43, v254, 14
	v_readlane_b32 s46, v254, 17
	v_readlane_b32 s47, v254, 18
	v_readlane_b32 s48, v254, 19
	v_readlane_b32 s49, v254, 20
	v_readlane_b32 s50, v254, 21
	v_readlane_b32 s51, v254, 22
	s_waitcnt vmcnt(43)
; DI float bflo(unsigned w) { return __uint_as_float(w << 16); }
; DI float bfhi(unsigned w) { return __uint_as_float(w & 0xffff0000u); }
; template <int DQK, int MODE>
; DI void attn_phase(const bf16_t* __restrict__ QK, int ldq, const bf16_t* __restrict__ Vt, int VC, bf16_t* __restrict__ O, int ldo, int nhu, bool skip_ctx, const float* __restrict__ qgain, const f32x2* __restrict__ rope, float qscale, char* shm) {
;     ...
;             float ss = 0.f;
; #pragma unroll
;             for (int ks = 0; ks < DQK / 16; ++ks) { const u32x4 wq = __builtin_bit_cast(u32x4, qf[ks]);
;                 const float a0 = bflo(wq.x), a1 = bfhi(wq.x), a2 = bflo(wq.y), a3 = bfhi(wq.y), a4 = bflo(wq.z), a5 = bfhi(wq.z), a6 = bflo(wq.w), a7 = bfhi(wq.w);
;                 ss += a0 * a0 + a1 * a1 + a2 * a2 + a3 * a3 + a4 * a4 + a5 * a5 + a6 * a6 + a7 * a7; }
;             ss += __shfl_xor(ss, 32);
;             const float rr = rsqrtf(ss * (1.f / DQK) + EPS) * qscale; int go = (MODE == 0 ? (hu & 1) * 64 : 0) + h * 8; asm volatile("" : "+v"(go));
;             const float* gq = qgain + go; const f32x2* rp = rope + (size_t)((qt > 0 ? qt - 1 : 0) * 256 + w * 32 + r) * (DQK / 2) + h * 8;
; #pragma unroll
;             for (int ks = 0; ks < DQK / 32; ++ks) {
;                 const u32x4 wa = __builtin_bit_cast(u32x4, qf[ks]), wb = __builtin_bit_cast(u32x4, qf[ks + DQK / 32]);
;                 float xa[8] = {bflo(wa.x), bfhi(wa.x), bflo(wa.y), bfhi(wa.y), bflo(wa.z), bfhi(wa.z), bflo(wa.w), bfhi(wa.w)};
;                 float xb[8] = {bflo(wb.x), bfhi(wb.x), bflo(wb.y), bfhi(wb.y), bflo(wb.z), bfhi(wb.z), bflo(wb.w), bfhi(wb.w)};
; #pragma unroll
;                 for (int j = 0; j < 8; ++j) { float x1 = xa[j] * rr * gq[ks * 16 + j], x2 = xb[j] * rr * gq[(ks + DQK / 32) * 16 + j];
;                     if (qt > 0) { const f32x2 cs = rp[ks * 16 + j]; const float y1 = x1 * cs[0] - x2 * cs[1], y2 = x1 * cs[1] + x2 * cs[0]; x1 = y1; x2 = y2; }
;                     xa[j] = x1; xb[j] = x2; }
	v_and_b32_e32 v7, 0xffff0000, v2
	s_waitcnt vmcnt(42)
	v_and_b32_e32 v6, 0xffff0000, v18
	v_lshlrev_b32_e32 v11, 16, v3
	s_waitcnt vmcnt(40)
	v_and_b32_e32 v32, 0xffff0000, v38
	v_and_b32_e32 v17, 0xffff0000, v3
	v_lshlrev_b32_e32 v31, 16, v5
	v_lshlrev_b32_e32 v30, 16, v21
	v_and_b32_e32 v35, 0xffff0000, v5
	v_and_b32_e32 v34, 0xffff0000, v21
	v_lshlrev_b32_e32 v36, 16, v38
	v_and_b32_e32 v33, 0xffff0000, v12
	v_lshlrev_b32_e32 v29, 16, v13
	v_and_b32_e32 v25, 0xffff0000, v13
	v_lshlrev_b32_e32 v21, 16, v14
	v_and_b32_e32 v13, 0xffff0000, v14
	v_lshlrev_b32_e32 v9, 16, v15
	v_and_b32_e32 v5, 0xffff0000, v15
	v_lshlrev_b32_e32 v3, 16, v2
	v_lshlrev_b32_e32 v2, 16, v18
	v_mov_b32_e32 v14, v6
	v_mov_b32_e32 v15, v32
	v_lshlrev_b32_e32 v10, 16, v19
	v_lshlrev_b32_e32 v37, 16, v12
	v_lshlrev_b32_e32 v28, 16, v39
	v_mov_b32_e32 v50, v2
	v_mov_b32_e32 v51, v36
	v_mov_b32_e32 v52, v7
	v_mov_b32_e32 v53, v33
	v_pk_mul_f32 v[14:15], v[14:15], v[14:15]
	v_and_b32_e32 v16, 0xffff0000, v19
	v_and_b32_e32 v24, 0xffff0000, v39
	v_mov_b32_e32 v18, v10
	v_mov_b32_e32 v19, v28
	v_mov_b32_e32 v66, v3
	v_mov_b32_e32 v67, v37
	v_pk_mul_f32 v[52:53], v[52:53], v[52:53]
	v_pk_fma_f32 v[14:15], v[50:51], v[50:51], v[14:15]
	v_lshlrev_b32_e32 v22, 16, v20
	v_and_b32_e32 v26, 0xffff0000, v20
	v_lshlrev_b32_e32 v20, 16, v40
	v_mov_b32_e32 v38, v16
	v_mov_b32_e32 v39, v24
	v_mov_b32_e32 v54, v11
	v_mov_b32_e32 v55, v29
	v_pk_fma_f32 v[50:51], v[66:67], v[66:67], v[52:53]
	v_pk_fma_f32 v[14:15], v[18:19], v[18:19], v[14:15]
	v_lshlrev_b32_e32 v23, 16, v4
	v_and_b32_e32 v27, 0xffff0000, v4
	v_and_b32_e32 v12, 0xffff0000, v40
	v_lshlrev_b32_e32 v8, 16, v41
	v_and_b32_e32 v4, 0xffff0000, v41
	v_mov_b32_e32 v40, v22
	v_mov_b32_e32 v41, v20
	v_mov_b32_e32 v56, v17
	v_mov_b32_e32 v57, v25
	v_pk_fma_f32 v[18:19], v[54:55], v[54:55], v[50:51]
	v_pk_fma_f32 v[14:15], v[38:39], v[38:39], v[14:15]
	v_mov_b32_e32 v44, v26
	v_mov_b32_e32 v45, v12
	v_mov_b32_e32 v58, v23
	v_mov_b32_e32 v59, v21
	v_pk_fma_f32 v[18:19], v[56:57], v[56:57], v[18:19]
	v_pk_fma_f32 v[14:15], v[40:41], v[40:41], v[14:15]
	v_mov_b32_e32 v46, v30
	v_mov_b32_e32 v47, v8
	v_mov_b32_e32 v60, v27
	v_mov_b32_e32 v61, v13
	v_pk_fma_f32 v[14:15], v[44:45], v[44:45], v[14:15]
	v_pk_fma_f32 v[18:19], v[58:59], v[58:59], v[18:19]
	v_mov_b32_e32 v48, v34
	v_mov_b32_e32 v49, v4
	v_mov_b32_e32 v62, v31
	v_mov_b32_e32 v63, v9
	v_pk_fma_f32 v[14:15], v[46:47], v[46:47], v[14:15]
	v_pk_fma_f32 v[18:19], v[60:61], v[60:61], v[18:19]
	v_mov_b32_e32 v64, v35
	v_mov_b32_e32 v65, v5
	v_pk_fma_f32 v[14:15], v[48:49], v[48:49], v[14:15]
	v_pk_fma_f32 v[18:19], v[62:63], v[62:63], v[18:19]
	v_add_f32_e32 v14, v14, v15
	v_pk_fma_f32 v[18:19], v[64:65], v[64:65], v[18:19]
	s_nop 0
	v_add_f32_e32 v14, v14, v18
	v_add_f32_e32 v15, v14, v19
	ds_bpermute_b32 v18, v127, v15
	v_lshl_add_u32 v14, s1, 8, v157
	s_waitcnt lgkmcnt(0)
	v_add_f32_e32 v15, v15, v18
	v_fmamk_f32 v15, v15, 0x3c800000, v164
	v_mul_f32_e32 v18, 0x4b800000, v15
	v_cmp_gt_f32_e32 vcc, s30, v15
	s_nop 1
	v_cndmask_b32_e32 v15, v15, v18, vcc
	v_rsq_f32_e32 v18, v15
	v_ashrrev_i32_e32 v15, 31, v14
	v_lshlrev_b64 v[14:15], 8, v[14:15]
	v_lshl_add_u64 v[14:15], v[130:131], 0, v[14:15]
	v_mul_f32_e32 v19, 0x45800000, v18
	v_cndmask_b32_e32 v18, v18, v19, vcc
	v_mul_f32_e32 v18, 0x3e38aa3b, v18
	v_pk_mul_f32 v[2:3], v[18:19], v[2:3] op_sel_hi:[0,1]
	s_waitcnt vmcnt(0)
	v_pk_mul_f32 v[2:3], v[200:201], v[2:3]
	s_cbranch_scc1 .LBB0_1294
	v_pk_mul_f32 v[42:43], v[2:3], v[168:169] op_sel:[1,1] op_sel_hi:[1,0]
	v_pk_mul_f32 v[40:41], v[2:3], v[168:169]
	v_pk_fma_f32 v[2:3], v[2:3], v[168:169], v[42:43] op_sel_hi:[0,1,1]
	v_sub_f32_e32 v2, v40, v42

; template <int DQK, int MODE>
; DI void attn_phase(const bf16_t* __restrict__ QK, int ldq, const bf16_t* __restrict__ Vt, int VC, bf16_t* __restrict__ O, int ldo, int nhu, bool skip_ctx, const float* __restrict__ qgain, const f32x2* __restrict__ rope, float qscale, char* shm) {
;     ...
;         f32x16 oacc[4];
; #pragma unroll
;         for (int t = 0; t < 4; ++t)
; #pragma unroll
;             for (int i = 0; i < 16; ++i) oacc[t][i] = 0.f;
;         float mrun = -1e30f, lsum = 0.f;
;         const bf16_t* kbase = QK + (size_t)b * LT * ldq + koff; const bf16_t* vbase = Vt + ((size_t)b * VC + voff) * LT;
;         u32x4 kreg[NKC], vreg[2];
;     ...
;         ATT_LOAD(0);
;     ...
;         __syncthreads();
;         ATT_STORE(0);
;         __syncthreads();
.LBB0_1326:
	s_ashr_i32 s11, s10, 31
	s_and_b32 s15, s12, 0xffffff80
	s_mul_i32 s35, s10, 0x900000
	s_mul_hi_i32 s34, s10, 0x900000
	s_add_u32 s36, s96, s35
	s_addc_u32 s37, s97, s34
	s_lshl_b64 s[0:1], s[12:13], 1
	s_add_u32 s12, s36, s0
	s_addc_u32 s13, s37, s1
	s_lshl_b64 s[10:11], s[10:11], 10
	s_ashr_i32 s36, s15, 31
	s_add_u32 s15, s10, s15
	s_addc_u32 s36, s11, s36
	v_lshl_add_u64 v[4:5], s[12:13], 0, v[132:133]
	v_mad_u64_u32 v[14:15], s[10:11], s15, v165, v[136:137]
	s_mulk_i32 s36, 0x1200
	v_lshl_add_u64 v[4:5], v[134:135], 1, v[4:5]
	v_add_u32_e32 v15, s36, v15
	v_lshl_add_u64 v[18:19], v[14:15], 0, v[138:139]
	v_lshl_add_u64 v[4:5], v[14:15], 0, v[140:141]
	v_cvt_pk_bf16_f32 v105, v10, v16
	v_cvt_pk_bf16_f32 v97, v11, v17
	v_add_u32_e32 v16, v159, v160
	v_add_u32_e32 v17, v159, v161
	s_sub_i32 s11, 0, s14
	v_mov_b32_e32 v14, v129
	v_mov_b32_e32 v15, v129
	v_add_u32_e32 v60, 0x2000, v16
	v_add_u32_e32 v61, 0x2000, v17
	s_add_u32 s0, s35, s0
	v_cvt_pk_bf16_f32 v104, v2, v6
	v_cvt_pk_bf16_f32 v106, v22, v26
	v_cvt_pk_bf16_f32 v107, v30, v34
	v_cvt_pk_bf16_f32 v96, v3, v7
	v_cvt_pk_bf16_f32 v98, v23, v27
	v_cvt_pk_bf16_f32 v99, v31, v35
	v_cvt_pk_bf16_f32 v108, v36, v32
	v_cvt_pk_bf16_f32 v109, v28, v24
	v_cvt_pk_bf16_f32 v110, v20, v12
	v_cvt_pk_bf16_f32 v111, v8, v0
	v_cvt_pk_bf16_f32 v100, v37, v33
	v_cvt_pk_bf16_f32 v101, v29, v25
	v_cvt_pk_bf16_f32 v102, v21, v13
	v_cvt_pk_bf16_f32 v103, v9, v1
	v_mov_b32_e32 v0, v129
	v_mov_b32_e32 v1, v129
	v_mov_b32_e32 v2, v129
	v_mov_b32_e32 v3, v129
	v_mov_b32_e32 v4, v129
	v_mov_b32_e32 v5, v129
	v_mov_b32_e32 v6, v129
	v_mov_b32_e32 v7, v129
	v_mov_b32_e32 v8, v129
	v_mov_b32_e32 v9, v129
	v_mov_b32_e32 v10, v129
	v_mov_b32_e32 v11, v129
	v_mov_b32_e32 v12, v129
	v_mov_b32_e32 v13, v129
	v_mov_b64_e32 v[30:31], v[14:15]
	v_mov_b64_e32 v[46:47], v[14:15]
	v_mad_u64_u32 v[150:151], s[12:13], s15, v165, v[142:143]
	v_mad_u64_u32 v[152:153], s[12:13], s15, v165, v[144:145]
	s_addc_u32 s1, s34, s1
	s_barrier
	s_mov_b32 s10, 1
	v_mov_b32_e32 v166, 0
	v_mov_b32_e32 v156, 0xf149f2ca
	v_mov_b64_e32 v[28:29], v[12:13]
	v_mov_b64_e32 v[26:27], v[10:11]
	v_mov_b64_e32 v[24:25], v[8:9]
	v_mov_b64_e32 v[22:23], v[6:7]
	v_mov_b64_e32 v[20:21], v[4:5]
	v_mov_b64_e32 v[18:19], v[2:3]
	v_mov_b64_e32 v[16:17], v[0:1]
	v_mov_b64_e32 v[44:45], v[12:13]
	v_mov_b64_e32 v[42:43], v[10:11]
	v_mov_b64_e32 v[40:41], v[8:9]
	v_mov_b64_e32 v[38:39], v[6:7]
	v_mov_b64_e32 v[36:37], v[4:5]
	v_mov_b64_e32 v[34:35], v[2:3]
	v_mov_b64_e32 v[32:33], v[0:1]
	v_add_u32_e32 v151, s36, v151
	s_waitcnt vmcnt(2)
	ds_write_b128 v158, v[232:235]
	s_waitcnt vmcnt(1)
	ds_write2_b64 v60, v[236:237], v[238:239] offset0:128 offset1:130
	s_waitcnt vmcnt(0)
	ds_write2_b64 v61, v[240:241], v[242:243] offset0:128 offset1:130
	v_mov_b64_e32 v[62:63], v[14:15]
	v_add_u32_e32 v153, s36, v153
	v_lshl_add_u64 v[154:155], v[146:147], 0, s[0:1]
	v_mov_b64_e32 v[60:61], v[12:13]
	v_mov_b64_e32 v[58:59], v[10:11]
	v_mov_b64_e32 v[56:57], v[8:9]
	v_mov_b64_e32 v[54:55], v[6:7]
	v_mov_b64_e32 v[52:53], v[4:5]
	v_mov_b64_e32 v[50:51], v[2:3]
	v_mov_b64_e32 v[48:49], v[0:1]
	s_waitcnt lgkmcnt(0)
	s_barrier
	s_branch .LBB0_1328
